# in-projection loop: DMA source addresses of the heavy load segments computed one segment early inside the MFMA segment (no setprio flips)
# speedup vs baseline: 1.0058x; 1.0050x over previous
; #define PG8_STAGE(bufoff, gbase, voff) do { _Pragma("unroll") for (int _i = 0; _i < 2; ++_i) \
;         __builtin_amdgcn_global_load_lds((const unsigned*)((const char*)(gbase) + (voff)[_i]), (LAS unsigned*)(lds + (bufoff) + ldsw + _i * 8192), 16, 0, 0); } while (0)
; #define PG8_LDA(dst, b, h) do { _Pragma("unroll") for (int m = 0; m < 4; ++m) _Pragma("unroll") for (int k = 0; k < 2; ++k) dst[m][k] = *(const LAS bf16x8*)(lds + PG8_SA(b, h) + aoff + m * 2048 + k * 1024); } while (0)
; #define PG8_LDB(dst, b, h) do { _Pragma("unroll") for (int n = 0; n < 2; ++n) _Pragma("unroll") for (int k = 0; k < 2; ++k) dst[n][k] = *(const LAS bf16x8*)(lds + PG8_SB(b, h) + boff + n * 2048 + k * 1024); } while (0)
; #define PG8_MMA(ai, bj, At, Bt) do { __builtin_amdgcn_s_setprio(1); _Pragma("unroll") for (int m = 0; m < 4; ++m) _Pragma("unroll") for (int n = 0; n < 2; ++n) _Pragma("unroll") for (int k = 0; k < 2; ++k) \
;         acc[ai][bj][m][n] = __builtin_amdgcn_mfma_f32_16x16x32_bf16(Bt[n][k], At[m][k], acc[ai][bj][m][n], 0, 0, 0); __builtin_amdgcn_s_setprio(0); } while (0)
; #define PG8_WAIT_V(n) asm volatile("s_waitcnt vmcnt(" #n ")" ::: "memory")
; #define PG8_WAIT_L(n) asm volatile("s_waitcnt lgkmcnt(" #n ")" ::: "memory")
; #define PG8_BAR __builtin_amdgcn_s_barrier()
; #define PG8_SCHED __builtin_amdgcn_sched_barrier(0)
; template <class Epi, class Sched>
; __device__ __forceinline__ void gemm_phase(LAS unsigned char* lds, const Gemm g, const Sched& S, const Epi& E, const int tid) {
;     ...
;             PG8_LDB(B0, 0, 0); PG8_LDB(B1, 0, 1); PG8_SCHED; PG8_LDA(At, 0, 0); PG8_STAGE(PG8_SA(1, 1), a1 + hstepA, voffA);
;             PG8_WAIT_V(8); PG8_WAIT_L(0); PG8_BAR; PG8_MMA(0, 0, At, B0); PG8_MMA(0, 1, At, B1); PG8_BAR; PG8_SCHED;
;             PG8_LDA(At, 0, 1); PG8_STAGE(PG8_SB(0, 0), b2, voffB); PG8_STAGE(PG8_SB(0, 1), b2 + hstepB, voffB); PG8_STAGE(PG8_SA(0, 0), a2, voffA);
;             PG8_WAIT_V(8); PG8_WAIT_L(0); PG8_BAR; PG8_MMA(1, 0, At, B0); PG8_MMA(1, 1, At, B1); PG8_BAR; PG8_SCHED;
.LBB0_347:
	s_add_u32 s24, s2, 0xfff80080
	s_addc_u32 s26, s3, -1
	s_add_i32 s31, 0, 0x10000
	s_cmp_eq_u32 s22, 28
	s_cselect_b32 s49, s15, s26
	s_cselect_b32 s48, s16, s24
	s_cselect_b32 s39, s11, s21
	s_cselect_b32 s38, s19, s20
	s_add_i32 s24, 0, 0x14000
	v_add_u32_e32 v140, s31, v158
	v_add_u32_e32 v154, s24, v158
	ds_read_b128 v[128:131], v140
	ds_read_b128 v[132:135], v140 offset:1024
	ds_read_b128 v[136:139], v140 offset:2048
	ds_read_b128 v[140:143], v140 offset:3072
	ds_read_b128 v[160:163], v154
	ds_read_b128 v[164:167], v154 offset:1024
	ds_read_b128 v[168:171], v154 offset:2048
	ds_read_b128 v[172:175], v154 offset:3072
	v_lshl_add_u64 v[154:155], s[2:3], 0, v[150:151]
	s_add_i32 m0, s45, 0xc000
	ds_read_b128 v[176:179], v159
	ds_read_b128 v[180:183], v159 offset:1024
	ds_read_b128 v[184:187], v159 offset:2048
	ds_read_b128 v[188:191], v159 offset:3072
	ds_read_b128 v[202:205], v159 offset:4096
	ds_read_b128 v[206:209], v159 offset:5120
	ds_read_b128 v[210:213], v159 offset:6144
	ds_read_b128 v[214:217], v159 offset:7168
	global_load_lds_dwordx4 v[154:155], off
	v_lshl_add_u64 v[154:155], s[2:3], 0, v[152:153]
	s_add_i32 m0, s45, 0xe000
	s_nop 0
	global_load_lds_dwordx4 v[154:155], off
	s_waitcnt vmcnt(8)
	s_waitcnt lgkmcnt(0)
	s_barrier
	s_waitcnt lgkmcnt(0)
	v_mfma_f32_16x16x32_bf16 v[124:127], v[128:131], v[176:179], v[124:127]
	v_mfma_f32_16x16x32_bf16 v[120:123], v[136:139], v[176:179], v[120:123]
	v_mfma_f32_16x16x32_bf16 v[108:111], v[128:131], v[184:187], v[108:111]
	v_lshl_add_u64 v[154:155], s[38:39], 0, v[192:193]
	v_mfma_f32_16x16x32_bf16 v[104:107], v[136:139], v[184:187], v[104:107]
	v_mfma_f32_16x16x32_bf16 v[92:95], v[128:131], v[202:205], v[92:95]
	v_mfma_f32_16x16x32_bf16 v[88:91], v[136:139], v[202:205], v[88:91]
	s_add_u32 s64, s38, 0x80000
	s_addc_u32 s65, s39, 0
	v_mfma_f32_16x16x32_bf16 v[76:79], v[128:131], v[210:213], v[76:79]
	v_mfma_f32_16x16x32_bf16 v[72:75], v[136:139], v[210:213], v[72:75]
	v_mfma_f32_16x16x32_bf16 v[124:127], v[132:135], v[180:183], v[124:127]
	v_lshl_add_u64 v[218:219], s[38:39], 0, v[148:149]
	v_mfma_f32_16x16x32_bf16 v[120:123], v[140:143], v[180:183], v[120:123]
	v_mfma_f32_16x16x32_bf16 v[108:111], v[132:135], v[188:191], v[108:111]
	v_mfma_f32_16x16x32_bf16 v[104:107], v[140:143], v[188:191], v[104:107]
	v_mfma_f32_16x16x32_bf16 v[92:95], v[132:135], v[206:209], v[92:95]
	v_lshl_add_u64 v[236:237], s[64:65], 0, v[192:193]
	v_mfma_f32_16x16x32_bf16 v[88:91], v[140:143], v[206:209], v[88:91]
	v_mfma_f32_16x16x32_bf16 v[76:79], v[132:135], v[214:217], v[76:79]
	v_mfma_f32_16x16x32_bf16 v[72:75], v[140:143], v[214:217], v[72:75]
	v_mfma_f32_16x16x32_bf16 v[116:119], v[160:163], v[176:179], v[116:119]
	v_mfma_f32_16x16x32_bf16 v[112:115], v[168:171], v[176:179], v[112:115]
	v_lshl_add_u64 v[238:239], s[64:65], 0, v[148:149]
	v_mfma_f32_16x16x32_bf16 v[100:103], v[160:163], v[184:187], v[100:103]
	v_mfma_f32_16x16x32_bf16 v[96:99], v[168:171], v[184:187], v[96:99]
	v_mfma_f32_16x16x32_bf16 v[84:87], v[160:163], v[202:205], v[84:87]
	v_mfma_f32_16x16x32_bf16 v[80:83], v[168:171], v[202:205], v[80:83]
	v_lshl_add_u64 v[220:221], s[48:49], 0, v[144:145]
	v_mfma_f32_16x16x32_bf16 v[68:71], v[160:163], v[210:213], v[68:71]
	v_mfma_f32_16x16x32_bf16 v[64:67], v[168:171], v[210:213], v[64:67]
	v_mfma_f32_16x16x32_bf16 v[116:119], v[164:167], v[180:183], v[116:119]
	v_mfma_f32_16x16x32_bf16 v[112:115], v[172:175], v[180:183], v[112:115]
	v_lshl_add_u64 v[222:223], s[48:49], 0, v[146:147]
	v_mfma_f32_16x16x32_bf16 v[100:103], v[164:167], v[188:191], v[100:103]
	v_mfma_f32_16x16x32_bf16 v[96:99], v[172:175], v[188:191], v[96:99]
	v_mfma_f32_16x16x32_bf16 v[84:87], v[164:167], v[206:209], v[84:87]
	v_mfma_f32_16x16x32_bf16 v[80:83], v[172:175], v[206:209], v[80:83]
	v_mfma_f32_16x16x32_bf16 v[68:71], v[164:167], v[214:217], v[68:71]
	v_mfma_f32_16x16x32_bf16 v[64:67], v[172:175], v[214:217], v[64:67]
	s_barrier
	s_add_i32 s26, s31, s25
	s_mov_b32 m0, s26
	ds_read_b128 v[176:179], v159 offset:16384
	ds_read_b128 v[180:183], v159 offset:17408
	ds_read_b128 v[184:187], v159 offset:18432
	ds_read_b128 v[188:191], v159 offset:19456
	ds_read_b128 v[202:205], v159 offset:20480
	ds_read_b128 v[206:209], v159 offset:21504
	ds_read_b128 v[210:213], v159 offset:22528
	ds_read_b128 v[214:217], v159 offset:23552
	global_load_lds_dwordx4 v[154:155], off
	s_add_i32 m0, s26, 0x2000
	s_add_i32 s24, s24, s25
	global_load_lds_dwordx4 v[218:219], off
	s_mov_b32 m0, s24
	s_nop 0
	global_load_lds_dwordx4 v[236:237], off
	s_add_i32 m0, s24, 0x2000
	s_nop 0
	global_load_lds_dwordx4 v[238:239], off
	s_mov_b32 m0, s45
	s_nop 0
	global_load_lds_dwordx4 v[220:221], off
	s_mov_b32 m0, s47
	s_nop 0
	global_load_lds_dwordx4 v[222:223], off
	s_waitcnt vmcnt(8)
	s_waitcnt lgkmcnt(0)
	s_barrier
; #define PG8_STAGE(bufoff, gbase, voff) do { _Pragma("unroll") for (int _i = 0; _i < 2; ++_i) \
;         __builtin_amdgcn_global_load_lds((const unsigned*)((const char*)(gbase) + (voff)[_i]), (LAS unsigned*)(lds + (bufoff) + ldsw + _i * 8192), 16, 0, 0); } while (0)
; #define PG8_LDA(dst, b, h) do { _Pragma("unroll") for (int m = 0; m < 4; ++m) _Pragma("unroll") for (int k = 0; k < 2; ++k) dst[m][k] = *(const LAS bf16x8*)(lds + PG8_SA(b, h) + aoff + m * 2048 + k * 1024); } while (0)
; #define PG8_LDB(dst, b, h) do { _Pragma("unroll") for (int n = 0; n < 2; ++n) _Pragma("unroll") for (int k = 0; k < 2; ++k) dst[n][k] = *(const LAS bf16x8*)(lds + PG8_SB(b, h) + boff + n * 2048 + k * 1024); } while (0)
; #define PG8_MMA(ai, bj, At, Bt) do { __builtin_amdgcn_s_setprio(1); _Pragma("unroll") for (int m = 0; m < 4; ++m) _Pragma("unroll") for (int n = 0; n < 2; ++n) _Pragma("unroll") for (int k = 0; k < 2; ++k) \
;         acc[ai][bj][m][n] = __builtin_amdgcn_mfma_f32_16x16x32_bf16(Bt[n][k], At[m][k], acc[ai][bj][m][n], 0, 0, 0); __builtin_amdgcn_s_setprio(0); } while (0)
; #define PG8_WAIT_V(n) asm volatile("s_waitcnt vmcnt(" #n ")" ::: "memory")
; #define PG8_WAIT_L(n) asm volatile("s_waitcnt lgkmcnt(" #n ")" ::: "memory")
; #define PG8_BAR __builtin_amdgcn_s_barrier()
; #define PG8_SCHED __builtin_amdgcn_sched_barrier(0)
; template <class Epi, class Sched>
; __device__ __forceinline__ void gemm_phase(LAS unsigned char* lds, const Gemm g, const Sched& S, const Epi& E, const int tid) {
;     ...
;             PG8_WAIT_V(8); PG8_WAIT_L(0); PG8_BAR; PG8_MMA(1, 0, At, B0); PG8_MMA(1, 1, At, B1); PG8_BAR; PG8_SCHED;
;             PG8_LDB(B0, 1, 0); PG8_LDB(B1, 1, 1); PG8_SCHED; PG8_LDA(At, 1, 0); PG8_STAGE(PG8_SA(0, 1), a2 + hstepA, voffA);
;             PG8_WAIT_V(8); PG8_WAIT_L(0); PG8_BAR; PG8_MMA(0, 0, At, B0); PG8_MMA(0, 1, At, B1); PG8_BAR; PG8_SCHED;
	s_waitcnt lgkmcnt(0)
	v_mfma_f32_16x16x32_bf16 v[60:63], v[128:131], v[176:179], v[60:63]
	v_mfma_f32_16x16x32_bf16 v[56:59], v[136:139], v[176:179], v[56:59]
	v_mfma_f32_16x16x32_bf16 v[44:47], v[128:131], v[184:187], v[44:47]
	v_mfma_f32_16x16x32_bf16 v[40:43], v[136:139], v[184:187], v[40:43]
	v_mfma_f32_16x16x32_bf16 v[28:31], v[128:131], v[202:205], v[28:31]
	v_mfma_f32_16x16x32_bf16 v[24:27], v[136:139], v[202:205], v[24:27]
	v_mfma_f32_16x16x32_bf16 v[12:15], v[128:131], v[210:213], v[12:15]
	v_mfma_f32_16x16x32_bf16 v[8:11], v[136:139], v[210:213], v[8:11]
	v_mfma_f32_16x16x32_bf16 v[60:63], v[132:135], v[180:183], v[60:63]
	v_mfma_f32_16x16x32_bf16 v[56:59], v[140:143], v[180:183], v[56:59]
	v_mfma_f32_16x16x32_bf16 v[44:47], v[132:135], v[188:191], v[44:47]
	v_mfma_f32_16x16x32_bf16 v[40:43], v[140:143], v[188:191], v[40:43]
	v_mfma_f32_16x16x32_bf16 v[28:31], v[132:135], v[206:209], v[28:31]
	v_mfma_f32_16x16x32_bf16 v[24:27], v[140:143], v[206:209], v[24:27]
	v_mfma_f32_16x16x32_bf16 v[12:15], v[132:135], v[214:217], v[12:15]
	v_mfma_f32_16x16x32_bf16 v[8:11], v[140:143], v[214:217], v[8:11]
	v_mfma_f32_16x16x32_bf16 v[52:55], v[160:163], v[176:179], v[52:55]
	v_mfma_f32_16x16x32_bf16 v[48:51], v[168:171], v[176:179], v[48:51]
	v_mfma_f32_16x16x32_bf16 v[36:39], v[160:163], v[184:187], v[36:39]
	v_mfma_f32_16x16x32_bf16 v[32:35], v[168:171], v[184:187], v[32:35]
	v_mfma_f32_16x16x32_bf16 v[20:23], v[160:163], v[202:205], v[20:23]
	v_mfma_f32_16x16x32_bf16 v[16:19], v[168:171], v[202:205], v[16:19]
	v_mfma_f32_16x16x32_bf16 v[4:7], v[160:163], v[210:213], v[4:7]
	v_mfma_f32_16x16x32_bf16 v[0:3], v[168:171], v[210:213], v[0:3]
	v_mfma_f32_16x16x32_bf16 v[52:55], v[164:167], v[180:183], v[52:55]
	v_mfma_f32_16x16x32_bf16 v[48:51], v[172:175], v[180:183], v[48:51]
	v_mfma_f32_16x16x32_bf16 v[36:39], v[164:167], v[188:191], v[36:39]
	v_mfma_f32_16x16x32_bf16 v[32:35], v[172:175], v[188:191], v[32:35]
	v_mfma_f32_16x16x32_bf16 v[20:23], v[164:167], v[206:209], v[20:23]
	v_mfma_f32_16x16x32_bf16 v[16:19], v[172:175], v[206:209], v[16:19]
	v_mfma_f32_16x16x32_bf16 v[4:7], v[164:167], v[214:217], v[4:7]
	v_mfma_f32_16x16x32_bf16 v[0:3], v[172:175], v[214:217], v[0:3]
	s_barrier
	s_add_i32 s24, 0, 0x18000
	s_add_i32 s26, 0, 0x1c000
	v_add_u32_e32 v140, s24, v158
	v_add_u32_e32 v172, s26, v158
	ds_read_b128 v[128:131], v140
	ds_read_b128 v[132:135], v140 offset:1024
	ds_read_b128 v[136:139], v140 offset:2048
	ds_read_b128 v[140:143], v140 offset:3072
	ds_read_b128 v[160:163], v172
	ds_read_b128 v[164:167], v172 offset:1024
	ds_read_b128 v[168:171], v172 offset:2048
	ds_read_b128 v[172:175], v172 offset:3072
	s_add_u32 s48, s48, 0x80000
	s_addc_u32 s49, s49, 0
	s_mov_b32 m0, s52
	v_lshl_add_u64 v[234:235], s[48:49], 0, v[144:145]
	ds_read_b128 v[176:179], v159 offset:32768
	ds_read_b128 v[180:183], v159 offset:33792
	ds_read_b128 v[184:187], v159 offset:34816
	ds_read_b128 v[188:191], v159 offset:35840
	ds_read_b128 v[202:205], v159 offset:36864
	ds_read_b128 v[206:209], v159 offset:37888
	ds_read_b128 v[210:213], v159 offset:38912
	ds_read_b128 v[214:217], v159 offset:39936
	global_load_lds_dwordx4 v[234:235], off
	v_lshl_add_u64 v[234:235], s[48:49], 0, v[146:147]
	s_mov_b32 m0, s53
	s_nop 0
	global_load_lds_dwordx4 v[234:235], off
	s_waitcnt vmcnt(8)
	s_waitcnt lgkmcnt(0)
	s_barrier
; #define PG8_STAGE(bufoff, gbase, voff) do { _Pragma("unroll") for (int _i = 0; _i < 2; ++_i) \
;         __builtin_amdgcn_global_load_lds((const unsigned*)((const char*)(gbase) + (voff)[_i]), (LAS unsigned*)(lds + (bufoff) + ldsw + _i * 8192), 16, 0, 0); } while (0)
; #define PG8_LDA(dst, b, h) do { _Pragma("unroll") for (int m = 0; m < 4; ++m) _Pragma("unroll") for (int k = 0; k < 2; ++k) dst[m][k] = *(const LAS bf16x8*)(lds + PG8_SA(b, h) + aoff + m * 2048 + k * 1024); } while (0)
; #define PG8_MMA(ai, bj, At, Bt) do { __builtin_amdgcn_s_setprio(1); _Pragma("unroll") for (int m = 0; m < 4; ++m) _Pragma("unroll") for (int n = 0; n < 2; ++n) _Pragma("unroll") for (int k = 0; k < 2; ++k) \
;         acc[ai][bj][m][n] = __builtin_amdgcn_mfma_f32_16x16x32_bf16(Bt[n][k], At[m][k], acc[ai][bj][m][n], 0, 0, 0); __builtin_amdgcn_s_setprio(0); } while (0)
; #define PG8_WAIT_V(n) asm volatile("s_waitcnt vmcnt(" #n ")" ::: "memory")
; #define PG8_WAIT_L(n) asm volatile("s_waitcnt lgkmcnt(" #n ")" ::: "memory")
; #define PG8_BAR __builtin_amdgcn_s_barrier()
; #define PG8_SCHED __builtin_amdgcn_sched_barrier(0)
; template <class Epi, class Sched>
; __device__ __forceinline__ void gemm_phase(LAS unsigned char* lds, const Gemm g, const Sched& S, const Epi& E, const int tid) {
;     ...
;             PG8_WAIT_V(8); PG8_WAIT_L(0); PG8_BAR; PG8_MMA(0, 0, At, B0); PG8_MMA(0, 1, At, B1); PG8_BAR; PG8_SCHED;
;             PG8_LDA(At, 1, 1); PG8_STAGE(PG8_SB(1, 0), b3, voffB); PG8_STAGE(PG8_SB(1, 1), b3 + hstepB, voffB); PG8_STAGE(PG8_SA(1, 0), a3, voffA);
;             PG8_WAIT_V(8); PG8_WAIT_L(0); PG8_BAR; PG8_MMA(1, 0, At, B0); PG8_MMA(1, 1, At, B1); PG8_BAR; PG8_SCHED;
;         }
	s_waitcnt lgkmcnt(0)
	v_mfma_f32_16x16x32_bf16 v[124:127], v[128:131], v[176:179], v[124:127]
	v_mfma_f32_16x16x32_bf16 v[120:123], v[136:139], v[176:179], v[120:123]
	v_mfma_f32_16x16x32_bf16 v[108:111], v[128:131], v[184:187], v[108:111]
	v_lshl_add_u64 v[154:155], v[154:155], 0, s[34:35]
	v_mfma_f32_16x16x32_bf16 v[104:107], v[136:139], v[184:187], v[104:107]
	v_mfma_f32_16x16x32_bf16 v[92:95], v[128:131], v[202:205], v[92:95]
	v_mfma_f32_16x16x32_bf16 v[88:91], v[136:139], v[202:205], v[88:91]
	s_add_u32 s38, s38, 0x80080
	s_addc_u32 s39, s39, 0
	v_mfma_f32_16x16x32_bf16 v[76:79], v[128:131], v[210:213], v[76:79]
	v_mfma_f32_16x16x32_bf16 v[72:75], v[136:139], v[210:213], v[72:75]
	v_mfma_f32_16x16x32_bf16 v[124:127], v[132:135], v[180:183], v[124:127]
	v_lshl_add_u64 v[240:241], v[218:219], 0, s[34:35]
	v_mfma_f32_16x16x32_bf16 v[120:123], v[140:143], v[180:183], v[120:123]
	v_mfma_f32_16x16x32_bf16 v[108:111], v[132:135], v[188:191], v[108:111]
	v_mfma_f32_16x16x32_bf16 v[104:107], v[140:143], v[188:191], v[104:107]
	v_mfma_f32_16x16x32_bf16 v[92:95], v[132:135], v[206:209], v[92:95]
	v_lshl_add_u64 v[242:243], s[38:39], 0, v[192:193]
	v_mfma_f32_16x16x32_bf16 v[88:91], v[140:143], v[206:209], v[88:91]
	v_mfma_f32_16x16x32_bf16 v[76:79], v[132:135], v[214:217], v[76:79]
	v_mfma_f32_16x16x32_bf16 v[72:75], v[140:143], v[214:217], v[72:75]
	v_mfma_f32_16x16x32_bf16 v[116:119], v[160:163], v[176:179], v[116:119]
	v_mfma_f32_16x16x32_bf16 v[112:115], v[168:171], v[176:179], v[112:115]
	v_lshl_add_u64 v[244:245], s[38:39], 0, v[148:149]
	v_mfma_f32_16x16x32_bf16 v[100:103], v[160:163], v[184:187], v[100:103]
	v_mfma_f32_16x16x32_bf16 v[96:99], v[168:171], v[184:187], v[96:99]
	v_mfma_f32_16x16x32_bf16 v[84:87], v[160:163], v[202:205], v[84:87]
	v_mfma_f32_16x16x32_bf16 v[80:83], v[168:171], v[202:205], v[80:83]
	v_lshl_add_u64 v[246:247], v[220:221], 0, s[34:35]
	v_mfma_f32_16x16x32_bf16 v[68:71], v[160:163], v[210:213], v[68:71]
	v_mfma_f32_16x16x32_bf16 v[64:67], v[168:171], v[210:213], v[64:67]
	v_mfma_f32_16x16x32_bf16 v[116:119], v[164:167], v[180:183], v[116:119]
	v_mfma_f32_16x16x32_bf16 v[112:115], v[172:175], v[180:183], v[112:115]
	v_lshl_add_u64 v[248:249], v[222:223], 0, s[34:35]
	v_mfma_f32_16x16x32_bf16 v[100:103], v[164:167], v[188:191], v[100:103]
	v_mfma_f32_16x16x32_bf16 v[96:99], v[172:175], v[188:191], v[96:99]
	v_mfma_f32_16x16x32_bf16 v[84:87], v[164:167], v[206:209], v[84:87]
	v_mfma_f32_16x16x32_bf16 v[80:83], v[172:175], v[206:209], v[80:83]
	v_mfma_f32_16x16x32_bf16 v[68:71], v[164:167], v[214:217], v[68:71]
	v_mfma_f32_16x16x32_bf16 v[64:67], v[172:175], v[214:217], v[64:67]
	s_barrier
	s_add_i32 s24, s24, s25
	s_mov_b32 m0, s24
	ds_read_b128 v[176:179], v159 offset:49152
	ds_read_b128 v[180:183], v159 offset:50176
	ds_read_b128 v[184:187], v159 offset:51200
	ds_read_b128 v[188:191], v159 offset:52224
	ds_read_b128 v[202:205], v159 offset:53248
	ds_read_b128 v[206:209], v159 offset:54272
	ds_read_b128 v[210:213], v159 offset:55296
	ds_read_b128 v[214:217], v159 offset:56320
	global_load_lds_dwordx4 v[154:155], off
	s_add_i32 m0, s24, 0x2000
	s_add_i32 s24, s26, s25
	global_load_lds_dwordx4 v[240:241], off
	s_mov_b32 m0, s24
	s_nop 0
	global_load_lds_dwordx4 v[242:243], off
	s_add_i32 m0, s24, 0x2000
	s_nop 0
	global_load_lds_dwordx4 v[244:245], off
	s_mov_b32 m0, s56
	s_nop 0
	global_load_lds_dwordx4 v[246:247], off
	s_mov_b32 m0, s57
	s_nop 0
	global_load_lds_dwordx4 v[248:249], off
	s_waitcnt vmcnt(8)
	s_waitcnt lgkmcnt(0)
	s_barrier
	s_waitcnt lgkmcnt(0)
	v_mfma_f32_16x16x32_bf16 v[60:63], v[128:131], v[176:179], v[60:63]
	v_mfma_f32_16x16x32_bf16 v[56:59], v[136:139], v[176:179], v[56:59]
	v_mfma_f32_16x16x32_bf16 v[44:47], v[128:131], v[184:187], v[44:47]
	v_mfma_f32_16x16x32_bf16 v[40:43], v[136:139], v[184:187], v[40:43]
	v_mfma_f32_16x16x32_bf16 v[28:31], v[128:131], v[202:205], v[28:31]
	v_mfma_f32_16x16x32_bf16 v[24:27], v[136:139], v[202:205], v[24:27]
	v_mfma_f32_16x16x32_bf16 v[12:15], v[128:131], v[210:213], v[12:15]
	v_mfma_f32_16x16x32_bf16 v[8:11], v[136:139], v[210:213], v[8:11]
	v_mfma_f32_16x16x32_bf16 v[60:63], v[132:135], v[180:183], v[60:63]
	v_mfma_f32_16x16x32_bf16 v[56:59], v[140:143], v[180:183], v[56:59]
	v_mfma_f32_16x16x32_bf16 v[44:47], v[132:135], v[188:191], v[44:47]
	v_mfma_f32_16x16x32_bf16 v[40:43], v[140:143], v[188:191], v[40:43]
	v_mfma_f32_16x16x32_bf16 v[28:31], v[132:135], v[206:209], v[28:31]
	v_mfma_f32_16x16x32_bf16 v[24:27], v[140:143], v[206:209], v[24:27]
	v_mfma_f32_16x16x32_bf16 v[12:15], v[132:135], v[214:217], v[12:15]
	v_mfma_f32_16x16x32_bf16 v[8:11], v[140:143], v[214:217], v[8:11]
	v_mfma_f32_16x16x32_bf16 v[52:55], v[160:163], v[176:179], v[52:55]
	v_mfma_f32_16x16x32_bf16 v[48:51], v[168:171], v[176:179], v[48:51]
	v_mfma_f32_16x16x32_bf16 v[36:39], v[160:163], v[184:187], v[36:39]
	v_mfma_f32_16x16x32_bf16 v[32:35], v[168:171], v[184:187], v[32:35]
	v_mfma_f32_16x16x32_bf16 v[20:23], v[160:163], v[202:205], v[20:23]
	v_mfma_f32_16x16x32_bf16 v[16:19], v[168:171], v[202:205], v[16:19]
	v_mfma_f32_16x16x32_bf16 v[4:7], v[160:163], v[210:213], v[4:7]
	v_mfma_f32_16x16x32_bf16 v[0:3], v[168:171], v[210:213], v[0:3]
	v_mfma_f32_16x16x32_bf16 v[52:55], v[164:167], v[180:183], v[52:55]
	v_mfma_f32_16x16x32_bf16 v[48:51], v[172:175], v[180:183], v[48:51]
	v_mfma_f32_16x16x32_bf16 v[36:39], v[164:167], v[188:191], v[36:39]
	v_mfma_f32_16x16x32_bf16 v[32:35], v[172:175], v[188:191], v[32:35]
	v_mfma_f32_16x16x32_bf16 v[20:23], v[164:167], v[206:209], v[20:23]
	v_mfma_f32_16x16x32_bf16 v[16:19], v[172:175], v[206:209], v[16:19]
	v_mfma_f32_16x16x32_bf16 v[4:7], v[164:167], v[214:217], v[4:7]
	v_mfma_f32_16x16x32_bf16 v[0:3], v[172:175], v[214:217], v[0:3]
	s_barrier
	s_add_i32 s22, s22, 2
	s_add_u32 s2, s2, 0x100
	s_addc_u32 s3, s3, 0
	s_add_u32 s20, s20, 0x100
	s_addc_u32 s21, s21, 0
	s_cmp_gt_u32 s22, 29
	s_cbranch_scc0 .LBB0_347
	s_and_b64 vcc, exec, s[8:9]
	s_cbranch_vccz .LBB0_350
	s_barrier
